# GEMM phases: one static s_setprio raise for the trailing half-workgroup instead of the per-block toggles
# baseline (speedup 1.0000x reference)
.LBB0_415:
	s_or_b64 exec, exec, s[20:21]
	s_cmp_eq_u32 s98, 2
	s_cselect_b64 s[8:9], -1, 0
	s_cmp_lg_u32 s98, 2
	s_cselect_b64 s[6:7], -1, 0
	v_mov_b32_e32 v2, v175
	s_and_b64 s[18:19], s[6:7], exec
	s_movk_i32 s5, 0x7e
	s_waitcnt lgkmcnt(0)
	s_barrier
	v_cmp_lt_u32_e32 vcc, 0xff, v175
	s_cbranch_vccz .Lg_noprio
	s_setprio 1
.Lg_noprio:
	s_cselect_b32 s5, s5, 0x7c
	v_readfirstlane_b32 s10, v2
	s_cmp_lt_i32 s98, 4
	s_cbranch_scc1 .LBB0_417
	s_cmp_eq_u32 s98, 4
	s_cselect_b64 s[18:19], -1, 0
	s_cbranch_execz .LBB0_418
	s_branch .LBB0_419

.LBB0_800:
	s_setprio 0
	s_mov_b64 exec, -1
	s_lshl_b32 s4, s86, 4
	s_add_u32 s4, s60, s4
	s_addc_u32 s5, s61, 0
	s_load_dwordx4 s[8:11], s[4:5], 0xc0
	v_readlane_b32 s6, v253, 3
	s_waitcnt lgkmcnt(0)
	s_cmp_eq_u32 s8, 0
	s_cbranch_scc0 .Ldf_done
	s_cmp_eq_u32 s10, 4
	s_cbranch_scc0 .Ldf_done
	s_cmp_lt_u32 s9, 3
	s_cbranch_scc0 .Ldf_done
	s_movk_i32 s7, 0xb58
